# GU GEMM main loop: LDS-DMA issues in saddr form (scalar base + loop-invariant VGPR offset), no 64-bit VALU address adds in the load segments
# speedup vs baseline: 1.0063x; 1.0063x over previous
; #define PG8_STAGE(bufoff, gbase, voff) do { _Pragma("unroll") for (int _i = 0; _i < 2; ++_i) \
;         __builtin_amdgcn_global_load_lds((const unsigned*)((const char*)(gbase) + (voff)[_i]), (LAS unsigned*)(lds + (bufoff) + ldsw + _i * 8192), 16, 0, 0); } while (0)
; #define PG8_LDA(dst, b, h) do { _Pragma("unroll") for (int m = 0; m < 4; ++m) _Pragma("unroll") for (int k = 0; k < 2; ++k) dst[m][k] = *(const LAS bf16x8*)(lds + PG8_SA(b, h) + aoff + m * 2048 + k * 1024); } while (0)
; #define PG8_LDB(dst, b, h) do { _Pragma("unroll") for (int n = 0; n < 2; ++n) _Pragma("unroll") for (int k = 0; k < 2; ++k) dst[n][k] = *(const LAS bf16x8*)(lds + PG8_SB(b, h) + boff + n * 2048 + k * 1024); } while (0)
; #define PG8_MMA(ai, bj, At, Bt) do { __builtin_amdgcn_s_setprio(1); _Pragma("unroll") for (int m = 0; m < 4; ++m) _Pragma("unroll") for (int n = 0; n < 2; ++n) _Pragma("unroll") for (int k = 0; k < 2; ++k) \
;         acc[ai][bj][m][n] = __builtin_amdgcn_mfma_f32_16x16x32_bf16(Bt[n][k], At[m][k], acc[ai][bj][m][n], 0, 0, 0); __builtin_amdgcn_s_setprio(0); } while (0)
; #define PG8_WAIT_V(n) asm volatile("s_waitcnt vmcnt(" #n ")" ::: "memory")
; #define PG8_BAR __builtin_amdgcn_s_barrier()
; template <class Epi, class Sched, bool ALIGN_EPI = false, bool SP2 = false>
; __device__ __forceinline__ void gemm_phase(LAS unsigned char* lds, const Gemm g, const Sched& S, const Epi& E, const int tid) {
;     ...
;         for (int t = 0; t < nt; t += 2) {
;             const bool last = (t == nt - 2);
;             const char* a1 = cA + (size_t)(t + 1) * kstep;
;             const char* a2 = last ? nA : cA + (size_t)(t + 2) * kstep; const char* b2 = last ? nB : cB + (size_t)(t + 2) * kstep;
;             const char* a3 = a2 + kstep; const char* b3 = b2 + kstep;
;             if (last && has_next) S.a_ready(nxt);
;             if constexpr (SP2) {
;             PG8_LDB(B0, 0, 0); PG8_LDB(B1, 0, 1); PG8_SCHED; PG8_LDA(At, 0, 0); PG8_STAGE(PG8_SA(1, 1), a1 + hstep, voffA);
;             PG8_WAIT_V(8); PG8_WAIT_L(0); PG8_BAR; PG8_MMA(0, 0, At, B0); PG8_MMA(0, 1, At, B1); PG8_BAR; PG8_SCHED;
;             PG8_LDA(At, 0, 1); PG8_STAGE(PG8_SB(0, 0), b2, voffB); PG8_STAGE(PG8_SB(0, 1), b2 + hstep, voffB); PG8_STAGE(PG8_SA(0, 0), a2, voffA);
;             PG8_WAIT_V(8); PG8_WAIT_L(0); PG8_BAR; PG8_MMA(1, 0, At, B0); PG8_MMA(1, 1, At, B1); PG8_BAR; PG8_SCHED;
.LBB0_427:
	s_add_u32 s20, s18, 0xfff80080
	s_addc_u32 s21, s19, -1
	s_add_i32 s43, 0, 0x10000
	s_cmp_eq_u32 s42, 28
	s_cselect_b32 s23, s11, s21
	s_cselect_b32 s22, s38, s20
	s_cselect_b32 s21, s9, s41
	s_cselect_b32 s20, s39, s40
	s_add_i32 s51, 0, 0x14000
	v_add_u32_e32 v166, s43, v151
	v_add_u32_e32 v182, s51, v151
	ds_read_b128 v[154:157], v166
	ds_read_b128 v[158:161], v166 offset:1024
	ds_read_b128 v[162:165], v166 offset:2048
	ds_read_b128 v[166:169], v166 offset:3072
	ds_read_b128 v[170:173], v182
	ds_read_b128 v[174:177], v182 offset:1024
	ds_read_b128 v[178:181], v182 offset:2048
	ds_read_b128 v[182:185], v182 offset:3072
	s_add_i32 m0, s17, 0xc000
	ds_read_b128 v[186:189], v153
	ds_read_b128 v[200:203], v153 offset:1024
	ds_read_b128 v[204:207], v153 offset:2048
	ds_read_b128 v[208:211], v153 offset:3072
	ds_read_b128 v[212:215], v153 offset:4096
	ds_read_b128 v[216:219], v153 offset:5120
	ds_read_b128 v[230:233], v153 offset:6144
	ds_read_b128 v[234:237], v153 offset:7168
	global_load_lds_dwordx4 v138, s[18:19]
	s_add_i32 m0, s17, 0xe000
	s_nop 0
	global_load_lds_dwordx4 v140, s[18:19]
	s_waitcnt vmcnt(8)
	s_waitcnt lgkmcnt(0)
	s_barrier
	s_setprio 1
	s_waitcnt lgkmcnt(0)
	v_mfma_f32_16x16x32_bf16 v[126:129], v[154:157], v[186:189], v[126:129]
	v_mfma_f32_16x16x32_bf16 v[122:125], v[162:165], v[186:189], v[122:125]
	v_mfma_f32_16x16x32_bf16 v[110:113], v[154:157], v[204:207], v[110:113]
	v_mfma_f32_16x16x32_bf16 v[106:109], v[162:165], v[204:207], v[106:109]
	v_mfma_f32_16x16x32_bf16 v[94:97], v[154:157], v[212:215], v[94:97]
	v_mfma_f32_16x16x32_bf16 v[90:93], v[162:165], v[212:215], v[90:93]
	v_mfma_f32_16x16x32_bf16 v[78:81], v[154:157], v[230:233], v[78:81]
	v_mfma_f32_16x16x32_bf16 v[74:77], v[162:165], v[230:233], v[74:77]
	v_mfma_f32_16x16x32_bf16 v[126:129], v[158:161], v[200:203], v[126:129]
	v_mfma_f32_16x16x32_bf16 v[122:125], v[166:169], v[200:203], v[122:125]
	v_mfma_f32_16x16x32_bf16 v[110:113], v[158:161], v[208:211], v[110:113]
	v_mfma_f32_16x16x32_bf16 v[106:109], v[166:169], v[208:211], v[106:109]
	v_mfma_f32_16x16x32_bf16 v[94:97], v[158:161], v[216:219], v[94:97]
	v_mfma_f32_16x16x32_bf16 v[90:93], v[166:169], v[216:219], v[90:93]
	v_mfma_f32_16x16x32_bf16 v[78:81], v[158:161], v[234:237], v[78:81]
	v_mfma_f32_16x16x32_bf16 v[74:77], v[166:169], v[234:237], v[74:77]
	s_setprio 0
	s_setprio 1
	v_mfma_f32_16x16x32_bf16 v[118:121], v[170:173], v[186:189], v[118:121]
	v_mfma_f32_16x16x32_bf16 v[114:117], v[178:181], v[186:189], v[114:117]
	v_mfma_f32_16x16x32_bf16 v[102:105], v[170:173], v[204:207], v[102:105]
	v_mfma_f32_16x16x32_bf16 v[98:101], v[178:181], v[204:207], v[98:101]
	v_mfma_f32_16x16x32_bf16 v[86:89], v[170:173], v[212:215], v[86:89]
	v_mfma_f32_16x16x32_bf16 v[82:85], v[178:181], v[212:215], v[82:85]
	v_mfma_f32_16x16x32_bf16 v[70:73], v[170:173], v[230:233], v[70:73]
	v_mfma_f32_16x16x32_bf16 v[66:69], v[178:181], v[230:233], v[66:69]
	v_mfma_f32_16x16x32_bf16 v[118:121], v[174:177], v[200:203], v[118:121]
	v_mfma_f32_16x16x32_bf16 v[114:117], v[182:185], v[200:203], v[114:117]
	v_mfma_f32_16x16x32_bf16 v[102:105], v[174:177], v[208:211], v[102:105]
	v_mfma_f32_16x16x32_bf16 v[98:101], v[182:185], v[208:211], v[98:101]
	v_mfma_f32_16x16x32_bf16 v[86:89], v[174:177], v[216:219], v[86:89]
	v_mfma_f32_16x16x32_bf16 v[82:85], v[182:185], v[216:219], v[82:85]
	v_mfma_f32_16x16x32_bf16 v[70:73], v[174:177], v[234:237], v[70:73]
	v_mfma_f32_16x16x32_bf16 v[66:69], v[182:185], v[234:237], v[66:69]
	s_setprio 0
	s_barrier
	s_add_i32 s43, s43, s26
	s_mov_b32 m0, s43
	ds_read_b128 v[186:189], v153 offset:16384
	ds_read_b128 v[200:203], v153 offset:17408
	ds_read_b128 v[204:207], v153 offset:18432
	ds_read_b128 v[208:211], v153 offset:19456
	ds_read_b128 v[212:215], v153 offset:20480
	ds_read_b128 v[216:219], v153 offset:21504
	ds_read_b128 v[230:233], v153 offset:22528
	ds_read_b128 v[234:237], v153 offset:23552
	global_load_lds_dwordx4 v134, s[20:21]
	s_add_i32 m0, s43, 0x2000
	s_add_u32 s54, s20, 0x80000
	s_addc_u32 s55, s21, 0
	s_add_i32 s43, s51, s26
	global_load_lds_dwordx4 v130, s[20:21]
	s_mov_b32 m0, s43
	s_nop 0
	global_load_lds_dwordx4 v134, s[54:55]
	s_add_i32 m0, s43, 0x2000
	s_nop 0
	global_load_lds_dwordx4 v130, s[54:55]
	s_mov_b32 m0, s17
	s_nop 0
	global_load_lds_dwordx4 v136, s[22:23]
	s_mov_b32 m0, s28
	s_nop 0
	global_load_lds_dwordx4 v132, s[22:23]
	s_waitcnt vmcnt(8)
	s_waitcnt lgkmcnt(0)
	s_barrier
	s_setprio 1
	s_waitcnt lgkmcnt(0)
	v_mfma_f32_16x16x32_bf16 v[62:65], v[154:157], v[186:189], v[62:65]
	v_mfma_f32_16x16x32_bf16 v[58:61], v[162:165], v[186:189], v[58:61]
	v_mfma_f32_16x16x32_bf16 v[46:49], v[154:157], v[204:207], v[46:49]
	v_mfma_f32_16x16x32_bf16 v[42:45], v[162:165], v[204:207], v[42:45]
	v_mfma_f32_16x16x32_bf16 v[30:33], v[154:157], v[212:215], v[30:33]
	v_mfma_f32_16x16x32_bf16 v[26:29], v[162:165], v[212:215], v[26:29]
	v_mfma_f32_16x16x32_bf16 v[14:17], v[154:157], v[230:233], v[14:17]
	v_mfma_f32_16x16x32_bf16 v[10:13], v[162:165], v[230:233], v[10:13]
	v_mfma_f32_16x16x32_bf16 v[62:65], v[158:161], v[200:203], v[62:65]
	v_mfma_f32_16x16x32_bf16 v[58:61], v[166:169], v[200:203], v[58:61]
	v_mfma_f32_16x16x32_bf16 v[46:49], v[158:161], v[208:211], v[46:49]
	v_mfma_f32_16x16x32_bf16 v[42:45], v[166:169], v[208:211], v[42:45]
	v_mfma_f32_16x16x32_bf16 v[30:33], v[158:161], v[216:219], v[30:33]
	v_mfma_f32_16x16x32_bf16 v[26:29], v[166:169], v[216:219], v[26:29]
	v_mfma_f32_16x16x32_bf16 v[14:17], v[158:161], v[234:237], v[14:17]
	v_mfma_f32_16x16x32_bf16 v[10:13], v[166:169], v[234:237], v[10:13]
	s_setprio 0
	s_setprio 1
	v_mfma_f32_16x16x32_bf16 v[54:57], v[170:173], v[186:189], v[54:57]
	v_mfma_f32_16x16x32_bf16 v[50:53], v[178:181], v[186:189], v[50:53]
	v_mfma_f32_16x16x32_bf16 v[38:41], v[170:173], v[204:207], v[38:41]
	v_mfma_f32_16x16x32_bf16 v[34:37], v[178:181], v[204:207], v[34:37]
	v_mfma_f32_16x16x32_bf16 v[22:25], v[170:173], v[212:215], v[22:25]
	v_mfma_f32_16x16x32_bf16 v[18:21], v[178:181], v[212:215], v[18:21]
	v_mfma_f32_16x16x32_bf16 v[6:9], v[170:173], v[230:233], v[6:9]
	v_mfma_f32_16x16x32_bf16 v[2:5], v[178:181], v[230:233], v[2:5]
	v_mfma_f32_16x16x32_bf16 v[54:57], v[174:177], v[200:203], v[54:57]
	v_mfma_f32_16x16x32_bf16 v[50:53], v[182:185], v[200:203], v[50:53]
	v_mfma_f32_16x16x32_bf16 v[38:41], v[174:177], v[208:211], v[38:41]
	v_mfma_f32_16x16x32_bf16 v[34:37], v[182:185], v[208:211], v[34:37]
	v_mfma_f32_16x16x32_bf16 v[22:25], v[174:177], v[216:219], v[22:25]
	v_mfma_f32_16x16x32_bf16 v[18:21], v[182:185], v[216:219], v[18:21]
	v_mfma_f32_16x16x32_bf16 v[6:9], v[174:177], v[234:237], v[6:9]
	v_mfma_f32_16x16x32_bf16 v[2:5], v[182:185], v[234:237], v[2:5]
	s_setprio 0
	s_barrier
; #define PG8_STAGE(bufoff, gbase, voff) do { _Pragma("unroll") for (int _i = 0; _i < 2; ++_i) \
;         __builtin_amdgcn_global_load_lds((const unsigned*)((const char*)(gbase) + (voff)[_i]), (LAS unsigned*)(lds + (bufoff) + ldsw + _i * 8192), 16, 0, 0); } while (0)
; #define PG8_LDA(dst, b, h) do { _Pragma("unroll") for (int m = 0; m < 4; ++m) _Pragma("unroll") for (int k = 0; k < 2; ++k) dst[m][k] = *(const LAS bf16x8*)(lds + PG8_SA(b, h) + aoff + m * 2048 + k * 1024); } while (0)
; #define PG8_LDB(dst, b, h) do { _Pragma("unroll") for (int n = 0; n < 2; ++n) _Pragma("unroll") for (int k = 0; k < 2; ++k) dst[n][k] = *(const LAS bf16x8*)(lds + PG8_SB(b, h) + boff + n * 2048 + k * 1024); } while (0)
; #define PG8_MMA(ai, bj, At, Bt) do { __builtin_amdgcn_s_setprio(1); _Pragma("unroll") for (int m = 0; m < 4; ++m) _Pragma("unroll") for (int n = 0; n < 2; ++n) _Pragma("unroll") for (int k = 0; k < 2; ++k) \
;         acc[ai][bj][m][n] = __builtin_amdgcn_mfma_f32_16x16x32_bf16(Bt[n][k], At[m][k], acc[ai][bj][m][n], 0, 0, 0); __builtin_amdgcn_s_setprio(0); } while (0)
; #define PG8_WAIT_V(n) asm volatile("s_waitcnt vmcnt(" #n ")" ::: "memory")
; #define PG8_WAIT_L(n) asm volatile("s_waitcnt lgkmcnt(" #n ")" ::: "memory")
; #define PG8_BAR __builtin_amdgcn_s_barrier()
; #define PG8_SCHED __builtin_amdgcn_sched_barrier(0)
; template <class Epi, class Sched, bool ALIGN_EPI = false, bool SP2 = false>
; __device__ __forceinline__ void gemm_phase(LAS unsigned char* lds, const Gemm g, const Sched& S, const Epi& E, const int tid) {
;     ...
;             PG8_LDB(B0, 1, 0); PG8_LDB(B1, 1, 1); PG8_SCHED; PG8_LDA(At, 1, 0); PG8_STAGE(PG8_SA(0, 1), a2 + hstep, voffA);
;             PG8_WAIT_V(8); PG8_WAIT_L(0); PG8_BAR; PG8_MMA(0, 0, At, B0); PG8_MMA(0, 1, At, B1); PG8_BAR; PG8_SCHED;
;             PG8_LDA(At, 1, 1); PG8_STAGE(PG8_SB(1, 0), b3, voffB); PG8_STAGE(PG8_SB(1, 1), b3 + hstep, voffB); PG8_STAGE(PG8_SA(1, 0), a3, voffA);
;             PG8_WAIT_V(8); PG8_WAIT_L(0); PG8_BAR; PG8_MMA(1, 0, At, B0); PG8_MMA(1, 1, At, B1); PG8_BAR; PG8_SCHED;
	s_add_i32 s43, 0, 0x18000
	s_add_i32 s51, 0, 0x1c000
	v_add_u32_e32 v166, s43, v151
	v_add_u32_e32 v182, s51, v151
	ds_read_b128 v[154:157], v166
	ds_read_b128 v[158:161], v166 offset:1024
	ds_read_b128 v[162:165], v166 offset:2048
	ds_read_b128 v[166:169], v166 offset:3072
	ds_read_b128 v[170:173], v182
	ds_read_b128 v[174:177], v182 offset:1024
	ds_read_b128 v[178:181], v182 offset:2048
	ds_read_b128 v[182:185], v182 offset:3072
	s_add_u32 s22, s22, 0x80000
	s_addc_u32 s23, s23, 0
	s_mov_b32 m0, s29
	ds_read_b128 v[186:189], v153 offset:32768
	ds_read_b128 v[200:203], v153 offset:33792
	ds_read_b128 v[204:207], v153 offset:34816
	ds_read_b128 v[208:211], v153 offset:35840
	ds_read_b128 v[212:215], v153 offset:36864
	ds_read_b128 v[216:219], v153 offset:37888
	ds_read_b128 v[230:233], v153 offset:38912
	ds_read_b128 v[234:237], v153 offset:39936
	global_load_lds_dwordx4 v136, s[22:23]
	s_mov_b32 m0, s30
	s_nop 0
	global_load_lds_dwordx4 v132, s[22:23]
	s_waitcnt vmcnt(8)
	s_waitcnt lgkmcnt(0)
	s_barrier
	s_setprio 1
	s_waitcnt lgkmcnt(0)
	v_mfma_f32_16x16x32_bf16 v[126:129], v[154:157], v[186:189], v[126:129]
	v_mfma_f32_16x16x32_bf16 v[122:125], v[162:165], v[186:189], v[122:125]
	v_mfma_f32_16x16x32_bf16 v[110:113], v[154:157], v[204:207], v[110:113]
	v_mfma_f32_16x16x32_bf16 v[106:109], v[162:165], v[204:207], v[106:109]
	v_mfma_f32_16x16x32_bf16 v[94:97], v[154:157], v[212:215], v[94:97]
	v_mfma_f32_16x16x32_bf16 v[90:93], v[162:165], v[212:215], v[90:93]
	v_mfma_f32_16x16x32_bf16 v[78:81], v[154:157], v[230:233], v[78:81]
	v_mfma_f32_16x16x32_bf16 v[74:77], v[162:165], v[230:233], v[74:77]
	v_mfma_f32_16x16x32_bf16 v[126:129], v[158:161], v[200:203], v[126:129]
	v_mfma_f32_16x16x32_bf16 v[122:125], v[166:169], v[200:203], v[122:125]
	v_mfma_f32_16x16x32_bf16 v[110:113], v[158:161], v[208:211], v[110:113]
	v_mfma_f32_16x16x32_bf16 v[106:109], v[166:169], v[208:211], v[106:109]
	v_mfma_f32_16x16x32_bf16 v[94:97], v[158:161], v[216:219], v[94:97]
	v_mfma_f32_16x16x32_bf16 v[90:93], v[166:169], v[216:219], v[90:93]
	v_mfma_f32_16x16x32_bf16 v[78:81], v[158:161], v[234:237], v[78:81]
	v_mfma_f32_16x16x32_bf16 v[74:77], v[166:169], v[234:237], v[74:77]
	s_setprio 0
	s_setprio 1
	v_mfma_f32_16x16x32_bf16 v[118:121], v[170:173], v[186:189], v[118:121]
	v_mfma_f32_16x16x32_bf16 v[114:117], v[178:181], v[186:189], v[114:117]
	v_mfma_f32_16x16x32_bf16 v[102:105], v[170:173], v[204:207], v[102:105]
	v_mfma_f32_16x16x32_bf16 v[98:101], v[178:181], v[204:207], v[98:101]
	v_mfma_f32_16x16x32_bf16 v[86:89], v[170:173], v[212:215], v[86:89]
	v_mfma_f32_16x16x32_bf16 v[82:85], v[178:181], v[212:215], v[82:85]
	v_mfma_f32_16x16x32_bf16 v[70:73], v[170:173], v[230:233], v[70:73]
	v_mfma_f32_16x16x32_bf16 v[66:69], v[178:181], v[230:233], v[66:69]
	v_mfma_f32_16x16x32_bf16 v[118:121], v[174:177], v[200:203], v[118:121]
	v_mfma_f32_16x16x32_bf16 v[114:117], v[182:185], v[200:203], v[114:117]
	v_mfma_f32_16x16x32_bf16 v[102:105], v[174:177], v[208:211], v[102:105]
	v_mfma_f32_16x16x32_bf16 v[98:101], v[182:185], v[208:211], v[98:101]
	v_mfma_f32_16x16x32_bf16 v[86:89], v[174:177], v[216:219], v[86:89]
	v_mfma_f32_16x16x32_bf16 v[82:85], v[182:185], v[216:219], v[82:85]
	v_mfma_f32_16x16x32_bf16 v[70:73], v[174:177], v[234:237], v[70:73]
	v_mfma_f32_16x16x32_bf16 v[66:69], v[182:185], v[234:237], v[66:69]
	s_setprio 0
	s_barrier
	s_add_i32 s32, s43, s26
	s_add_u32 s20, s20, 0x80
	s_addc_u32 s21, s21, 0
	s_mov_b32 m0, s32
	ds_read_b128 v[186:189], v153 offset:49152
	ds_read_b128 v[200:203], v153 offset:50176
	ds_read_b128 v[204:207], v153 offset:51200
	ds_read_b128 v[208:211], v153 offset:52224
	ds_read_b128 v[212:215], v153 offset:53248
	ds_read_b128 v[216:219], v153 offset:54272
	ds_read_b128 v[230:233], v153 offset:55296
	ds_read_b128 v[234:237], v153 offset:56320
	global_load_lds_dwordx4 v134, s[20:21]
	s_add_i32 m0, s32, 0x2000
	s_add_i32 s32, s51, s26
	global_load_lds_dwordx4 v130, s[20:21]
	s_add_u32 s20, s20, 0x80000
	s_addc_u32 s21, s21, 0
	s_mov_b32 m0, s32
	s_nop 0
	global_load_lds_dwordx4 v134, s[20:21]
	s_add_i32 m0, s32, 0x2000
	s_add_u32 s22, s22, 0xfff80080
	s_addc_u32 s23, s23, -1
	global_load_lds_dwordx4 v130, s[20:21]
	s_mov_b32 m0, s31
	s_nop 0
	global_load_lds_dwordx4 v136, s[22:23]
	s_mov_b32 m0, s34
	s_nop 0
	global_load_lds_dwordx4 v132, s[22:23]
	s_waitcnt vmcnt(8)
	s_waitcnt lgkmcnt(0)
	s_barrier
	s_setprio 1
	s_waitcnt lgkmcnt(0)
	v_mfma_f32_16x16x32_bf16 v[62:65], v[154:157], v[186:189], v[62:65]
	v_mfma_f32_16x16x32_bf16 v[58:61], v[162:165], v[186:189], v[58:61]
	v_mfma_f32_16x16x32_bf16 v[46:49], v[154:157], v[204:207], v[46:49]
	v_mfma_f32_16x16x32_bf16 v[42:45], v[162:165], v[204:207], v[42:45]
	v_mfma_f32_16x16x32_bf16 v[30:33], v[154:157], v[212:215], v[30:33]
	v_mfma_f32_16x16x32_bf16 v[26:29], v[162:165], v[212:215], v[26:29]
	v_mfma_f32_16x16x32_bf16 v[14:17], v[154:157], v[230:233], v[14:17]
	v_mfma_f32_16x16x32_bf16 v[10:13], v[162:165], v[230:233], v[10:13]
	v_mfma_f32_16x16x32_bf16 v[62:65], v[158:161], v[200:203], v[62:65]
	v_mfma_f32_16x16x32_bf16 v[58:61], v[166:169], v[200:203], v[58:61]
	v_mfma_f32_16x16x32_bf16 v[46:49], v[158:161], v[208:211], v[46:49]
	v_mfma_f32_16x16x32_bf16 v[42:45], v[166:169], v[208:211], v[42:45]
	v_mfma_f32_16x16x32_bf16 v[30:33], v[158:161], v[216:219], v[30:33]
	v_mfma_f32_16x16x32_bf16 v[26:29], v[166:169], v[216:219], v[26:29]
	v_mfma_f32_16x16x32_bf16 v[14:17], v[158:161], v[234:237], v[14:17]
	v_mfma_f32_16x16x32_bf16 v[10:13], v[166:169], v[234:237], v[10:13]
	s_setprio 0
	s_setprio 1
	v_mfma_f32_16x16x32_bf16 v[54:57], v[170:173], v[186:189], v[54:57]
	v_mfma_f32_16x16x32_bf16 v[50:53], v[178:181], v[186:189], v[50:53]
	v_mfma_f32_16x16x32_bf16 v[38:41], v[170:173], v[204:207], v[38:41]
	v_mfma_f32_16x16x32_bf16 v[34:37], v[178:181], v[204:207], v[34:37]
	v_mfma_f32_16x16x32_bf16 v[22:25], v[170:173], v[212:215], v[22:25]
	v_mfma_f32_16x16x32_bf16 v[18:21], v[178:181], v[212:215], v[18:21]
	v_mfma_f32_16x16x32_bf16 v[6:9], v[170:173], v[230:233], v[6:9]
	v_mfma_f32_16x16x32_bf16 v[2:5], v[178:181], v[230:233], v[2:5]
	v_mfma_f32_16x16x32_bf16 v[54:57], v[174:177], v[200:203], v[54:57]
	v_mfma_f32_16x16x32_bf16 v[50:53], v[182:185], v[200:203], v[50:53]
	v_mfma_f32_16x16x32_bf16 v[38:41], v[174:177], v[208:211], v[38:41]
	v_mfma_f32_16x16x32_bf16 v[34:37], v[182:185], v[208:211], v[34:37]
	v_mfma_f32_16x16x32_bf16 v[22:25], v[174:177], v[216:219], v[22:25]
	v_mfma_f32_16x16x32_bf16 v[18:21], v[182:185], v[216:219], v[18:21]
	v_mfma_f32_16x16x32_bf16 v[6:9], v[174:177], v[234:237], v[6:9]
	v_mfma_f32_16x16x32_bf16 v[2:5], v[182:185], v[234:237], v[2:5]
	s_setprio 0
	s_barrier
	s_add_i32 s42, s42, 2
	s_add_u32 s18, s18, 0x100
	s_addc_u32 s19, s19, 0
	s_add_u32 s40, s40, 0x100
	s_addc_u32 s41, s41, 0
	s_cmp_gt_u32 s42, 29
	s_cbranch_scc0 .LBB0_427
	s_and_b64 vcc, exec, s[4:5]
	s_cbranch_vccz .LBB0_430
	s_barrier
